# E53: FoX unit prologues (prompt + sample): second wave-index lookup done with ds_read_b32 instead of a flat load + vmcnt(0), so the forget-bias loads are issued while the Q/K/V loads are still in flig
# speedup vs baseline: 1.0003x; 1.0003x over previous
.LBB0_1338:
	s_lshl_b64 s[16:17], s[60:61], 10
	s_mov_b64 s[14:15], src_shared_base
	s_add_u32 s6, s59, s16
	s_addc_u32 s14, s50, s17
	s_lshl_b64 s[96:97], s[18:19], 1
	s_add_u32 s94, s6, s96
	s_getreg_b32 s6, hwreg(HW_REG_HW_ID, 0, 6)
	s_addc_u32 s95, s14, s97
	s_and_b32 s6, s6, 63
	s_lshl_b32 s6, s6, 2
	s_add_i32 s6, s6, 0
	s_add_i32 s6, s6, 0x23e00
	v_mov_b32_e32 v4, s6
	v_mov_b32_e32 v5, s15
	flat_load_dword v172, v[4:5] sc0 sc1
	s_waitcnt vmcnt(0)
	s_add_i32 s6, s12, -1
	s_cmpk_gt_i32 s13, 0x1ff
	s_mov_b64 s[18:19], -1
	s_cbranch_scc1 .LBB0_1403
	s_waitcnt lgkmcnt(0)
	v_readfirstlane_b32 s13, v172
	v_mov_b32_e32 v153, v3
	s_mov_b64 s[14:15], src_shared_base
	v_lshl_add_u32 v2, s13, 6, v217
	v_mov_b32_e32 v19, 0
	v_readfirstlane_b32 s13, v2
	s_ashr_i32 s13, s13, 1
	s_andn2_b32 s13, s13, 31
	v_or_b32_e32 v146, s13, v212
	v_min_i32_e32 v4, s6, v146
	v_ashrrev_i32_e32 v5, 31, v4
	v_lshlrev_b64 v[4:5], 10, v[4:5]
	v_lshl_add_u64 v[4:5], s[94:95], 0, v[4:5]
	v_lshl_add_u64 v[4:5], v[4:5], 0, v[152:153]
	global_load_dwordx4 v[114:117], v[4:5], off
	global_load_dwordx4 v[118:121], v[4:5], off offset:32
	global_load_dwordx4 v[122:125], v[4:5], off offset:64
	global_load_dwordx4 v[126:129], v[4:5], off offset:96
	v_ashrrev_i32_e32 v4, 31, v2
	v_lshrrev_b32_e32 v4, 29, v4
	v_add_u32_e32 v5, v2, v4
	v_ashrrev_i32_e32 v4, 3, v5
	v_and_b32_e32 v5, -8, v5
	v_sub_u32_e32 v8, v2, v5
	v_ashrrev_i32_e32 v5, 31, v4
	v_lshlrev_b32_e32 v148, 3, v8
	v_lshlrev_b64 v[6:7], 9, v[4:5]
	v_ashrrev_i32_e32 v149, 31, v148
	v_lshl_add_u64 v[6:7], v[6:7], 0, v[148:149]
	v_lshlrev_b64 v[6:7], 1, v[6:7]
	v_lshl_add_u64 v[10:11], s[64:65], 0, v[6:7]
	v_lshl_add_u64 v[6:7], s[66:67], 0, v[6:7]
	v_add_u32_e32 v5, 0x200, v2
	global_load_dwordx4 v[134:137], v[6:7], off
	v_ashrrev_i32_e32 v6, 31, v5
	v_lshrrev_b32_e32 v6, 29, v6
	v_add_u32_e32 v7, v5, v6
	v_ashrrev_i32_e32 v6, 3, v7
	v_and_b32_e32 v7, -8, v7
	v_sub_u32_e32 v5, v5, v7
	v_ashrrev_i32_e32 v7, 31, v6
	v_lshlrev_b32_e32 v156, 3, v5
	global_load_dwordx4 v[130:133], v[10:11], off
	v_lshlrev_b64 v[10:11], 9, v[6:7]
	v_ashrrev_i32_e32 v157, 31, v156
	v_lshl_add_u64 v[10:11], v[10:11], 0, v[156:157]
	v_lshlrev_b64 v[10:11], 1, v[10:11]
	v_lshl_add_u64 v[12:13], s[64:65], 0, v[10:11]
	v_lshl_add_u64 v[10:11], s[66:67], 0, v[10:11]
	global_load_dwordx4 v[138:141], v[12:13], off
	global_load_dwordx4 v[142:145], v[10:11], off
	s_getreg_b32 s14, hwreg(HW_REG_HW_ID, 0, 6)
	s_and_b32 s14, s14, 63
	s_lshl_b32 s14, s14, 2
	s_add_i32 s14, s14, 0
	s_add_i32 s14, s14, 0x23e00
	v_mov_b32_e32 v10, s14
	v_mov_b32_e32 v11, s15
	ds_read_b32 v7, v10
	s_nop 0
	v_mov_b32_e32 v10, 0
	s_waitcnt lgkmcnt(0)
	v_readfirstlane_b32 s14, v7
	s_nop 1
	v_lshl_add_u32 v13, s14, 6, v217
	v_lshl_add_u32 v7, v13, 3, v13
	v_cmp_gt_i32_e32 vcc, s9, v7
	v_mov_b32_e32 v199, 0
	s_and_saveexec_b64 s[20:21], vcc
	s_cbranch_execz .LBB0_1341
	v_mov_b32_e32 v9, s93
	v_mov_b32_e32 v10, s79
	v_cmp_gt_i32_e64 s[18:19], s11, v7
	v_subrev_u32_e32 v12, s11, v7
	s_nop 0
	v_cndmask_b32_e64 v11, v9, v10, s[18:19]
	v_mov_b32_e32 v9, s92
	v_mov_b32_e32 v10, s78
	v_cndmask_b32_e64 v10, v9, v10, s[18:19]
	v_ashrrev_i32_e32 v9, 31, v7
	v_cndmask_b32_e64 v15, 0, v9, s[18:19]
	v_cndmask_b32_e64 v14, v12, v7, s[18:19]
	v_lshlrev_b64 v[14:15], 5, v[14:15]
	v_lshl_add_u64 v[10:11], v[10:11], 0, v[14:15]
	global_load_dword v199, v[10:11], off

.LBB0_1403:
	s_and_b64 vcc, exec, s[18:19]
	s_cbranch_vccz .LBB0_1227
	s_waitcnt lgkmcnt(0)
	v_readfirstlane_b32 s13, v172
	v_mov_b32_e32 v153, v3
	s_mov_b64 s[18:19], src_shared_base
	v_lshl_add_u32 v2, s13, 6, v217
	v_mov_b32_e32 v17, 0
	v_readfirstlane_b32 s13, v2
	s_ashr_i32 s90, s13, 1
	s_andn2_b32 s90, s90, 31
	v_or_b32_e32 v118, s90, v212
	v_min_i32_e32 v4, s6, v118
	v_ashrrev_i32_e32 v5, 31, v4
	v_lshlrev_b64 v[4:5], 10, v[4:5]
	v_lshl_add_u64 v[4:5], s[94:95], 0, v[4:5]
	v_lshl_add_u64 v[4:5], v[4:5], 0, v[152:153]
	global_load_dwordx4 v[94:97], v[4:5], off
	global_load_dwordx4 v[90:93], v[4:5], off offset:32
	global_load_dwordx4 v[86:89], v[4:5], off offset:64
	global_load_dwordx4 v[82:85], v[4:5], off offset:96
	v_ashrrev_i32_e32 v4, 31, v2
	v_lshrrev_b32_e32 v4, 29, v4
	v_add_u32_e32 v5, v2, v4
	v_ashrrev_i32_e32 v4, 3, v5
	v_and_b32_e32 v5, -8, v5
	v_sub_u32_e32 v6, v2, v5
	v_ashrrev_i32_e32 v5, 31, v4
	v_lshlrev_b32_e32 v120, 3, v6
	v_lshlrev_b64 v[8:9], 9, v[4:5]
	v_ashrrev_i32_e32 v121, 31, v120
	v_lshl_add_u64 v[8:9], v[8:9], 0, v[120:121]
	v_lshlrev_b64 v[8:9], 2, v[8:9]
	v_lshl_add_u64 v[10:11], s[68:69], 0, v[8:9]
	v_lshl_add_u64 v[8:9], s[76:77], 0, v[8:9]
	global_load_dwordx4 v[98:101], v[10:11], off offset:16 nt
	global_load_dwordx4 v[102:105], v[10:11], off nt
	global_load_dwordx4 v[106:109], v[8:9], off offset:16 nt
	global_load_dwordx4 v[110:113], v[8:9], off nt
	s_getreg_b32 s6, hwreg(HW_REG_HW_ID, 0, 6)
	s_and_b32 s6, s6, 63
	s_lshl_b32 s6, s6, 2
	s_add_i32 s6, s6, 0
	s_add_i32 s6, s6, 0x23e00
	v_mov_b32_e32 v8, s6
	v_mov_b32_e32 v9, s19
	ds_read_b32 v5, v8
	s_nop 0
	v_mov_b32_e32 v8, 0
	s_waitcnt lgkmcnt(0)
	v_readfirstlane_b32 s6, v5
	s_nop 1
	v_lshl_add_u32 v9, s6, 6, v217
	v_lshl_add_u32 v5, v9, 3, v9
	v_cmp_gt_i32_e32 vcc, s9, v5
	v_mov_b32_e32 v200, 0
	s_and_saveexec_b64 s[20:21], vcc
	s_cbranch_execz .LBB0_1406
	v_mov_b32_e32 v7, s93
	v_mov_b32_e32 v8, s79
	v_cmp_gt_i32_e64 s[18:19], s11, v5
	s_nop 1
	v_cndmask_b32_e64 v11, v7, v8, s[18:19]
	v_mov_b32_e32 v7, s92
	v_mov_b32_e32 v8, s78
	v_cndmask_b32_e64 v10, v7, v8, s[18:19]
	v_ashrrev_i32_e32 v7, 31, v5
	v_subrev_u32_e32 v8, s11, v5
	v_cndmask_b32_e64 v13, 0, v7, s[18:19]
	v_cndmask_b32_e64 v12, v8, v5, s[18:19]
	v_lshlrev_b64 v[12:13], 5, v[12:13]
	v_lshl_add_u64 v[10:11], v[10:11], 0, v[12:13]
	global_load_dword v200, v[10:11], off
